# pool-weight fold loops: pool_w rows prefetched one 8-row step ahead into spare VGPRs (was: load + immediate vmcnt ladder every iteration), both layer copies
# speedup vs baseline: 1.0073x; 1.0073x over previous
; #define LAS __attribute__((address_space(3)))
; __device__ __forceinline__ void phase_convert(PP p, int l, LAS unsigned char* lds, int tid, int lane, int wave) {
;     ...
;         for (int item = blockIdx.x; item < 256; item += gridDim.x) {
;             const int kb = item >> 2, g = item & 3, k0 = kb * 32;
;             for (int i = tid; i < 32 * 256; i += 512) { const int r = i >> 8, cc = i & 255; AtT[cc * 36 + r] = w_in[(size_t)(k0 + r) * INP + g * 256 + cc]; }
;             __syncthreads();
;             const int d = (wave & 3) * 64 + lane, kh = (wave >> 2) * 16;
;             float acc[16];
; #pragma unroll
;             for (int e = 0; e < 16; ++e) acc[e] = 0.f;
;             const float* pw = pool_w + (size_t)g * 65536 + d;
; #pragma unroll 8
;             for (int c = 0; c < 256; ++c) { const float bw = pw[c * 256];
; #pragma unroll
;                 for (int q = 0; q < 4; ++q) { const f32x4 a4 = *(const LAS f32x4*)(AtT + c * 36 + kh + 4 * q);
;                     acc[4 * q] += a4.x * bw; acc[4 * q + 1] += a4.y * bw; acc[4 * q + 2] += a4.z * bw; acc[4 * q + 3] += a4.w * bw; } }
.LBB0_39:
	s_or_b64 exec, exec, s[26:27]
	s_and_b32 s10, s38, 3
	s_lshl_b32 s22, s10, 18
	v_mov_b32_e32 v12, 0
	v_lshl_add_u64 v[10:11], v[8:9], 0, s[22:23]
	s_mov_b64 s[26:27], 0
	s_mov_b32 s22, s0
	v_mov_b32_e32 v13, v12
	v_mov_b32_e32 v16, v12
	v_mov_b32_e32 v17, v12
	v_mov_b32_e32 v20, v12
	v_mov_b32_e32 v21, v12
	v_mov_b32_e32 v24, v12
	v_mov_b32_e32 v25, v12
	v_mov_b32_e32 v26, v12
	v_mov_b32_e32 v27, v12
	v_mov_b32_e32 v14, v12
	v_mov_b32_e32 v15, v12
	v_mov_b32_e32 v18, v12
	v_mov_b32_e32 v19, v12
	v_mov_b32_e32 v22, v12
	v_mov_b32_e32 v23, v12
	s_waitcnt lgkmcnt(0)
	s_barrier
	s_mov_b32 s100, 0x1000
	s_mov_b32 s101, 0
	v_lshl_add_u64 v[188:189], v[10:11], 0, s[26:27]
	v_lshl_add_u64 v[188:189], v[188:189], 0, s[100:101]
	global_load_dword v180, v[188:189], off offset:-4096
	global_load_dword v181, v[188:189], off offset:-3072
	global_load_dword v182, v[188:189], off offset:-2048
	global_load_dword v183, v[188:189], off offset:-1024
	global_load_dword v184, v[188:189], off offset:0
	global_load_dword v185, v[188:189], off offset:1024
	global_load_dword v186, v[188:189], off offset:2048
	global_load_dword v187, v[188:189], off offset:3072
.LBB0_40:
	s_waitcnt vmcnt(0)
	v_mov_b32_e32 v160, v180
	v_mov_b32_e32 v162, v181
	v_mov_b32_e32 v164, v182
	v_mov_b32_e32 v166, v183
	v_mov_b32_e32 v168, v184
	v_mov_b32_e32 v170, v185
	v_mov_b32_e32 v172, v186
	v_mov_b32_e32 v174, v187
	s_add_u32 s98, s26, 0x2000
	s_cmp_eq_u32 s98, 0x40000
	s_cselect_b32 s98, s26, s98
	s_mov_b32 s99, 0
	v_lshl_add_u64 v[188:189], v[10:11], 0, s[98:99]
	v_lshl_add_u64 v[188:189], v[188:189], 0, s[100:101]
	global_load_dword v180, v[188:189], off offset:-4096
	global_load_dword v181, v[188:189], off offset:-3072
	global_load_dword v182, v[188:189], off offset:-2048
	global_load_dword v183, v[188:189], off offset:-1024
	global_load_dword v184, v[188:189], off offset:0
	global_load_dword v185, v[188:189], off offset:1024
	global_load_dword v186, v[188:189], off offset:2048
	global_load_dword v187, v[188:189], off offset:3072
	v_mov_b32_e32 v5, s22
	ds_read_b128 v[32:35], v5
	ds_read_b128 v[36:39], v5 offset:16
	ds_read_b128 v[40:43], v5 offset:32
	ds_read_b128 v[44:47], v5 offset:48
	ds_read_b128 v[48:51], v5 offset:144
	ds_read_b128 v[52:55], v5 offset:160
	ds_read_b128 v[56:59], v5 offset:176
	ds_read_b128 v[60:63], v5 offset:192
	ds_read_b128 v[64:67], v5 offset:288
	ds_read_b128 v[68:71], v5 offset:304
	ds_read_b128 v[72:75], v5 offset:320
	ds_read_b128 v[76:79], v5 offset:336
	ds_read_b128 v[80:83], v5 offset:432
	ds_read_b128 v[84:87], v5 offset:448
	ds_read_b128 v[88:91], v5 offset:464
	ds_read_b128 v[92:95], v5 offset:480
	ds_read_b128 v[96:99], v5 offset:576
	ds_read_b128 v[100:103], v5 offset:592
	ds_read_b128 v[104:107], v5 offset:608
	ds_read_b128 v[108:111], v5 offset:624
	ds_read_b128 v[112:115], v5 offset:720
	ds_read_b128 v[116:119], v5 offset:736
	ds_read_b128 v[120:123], v5 offset:752
	ds_read_b128 v[124:127], v5 offset:768
	ds_read_b128 v[128:131], v5 offset:864
	ds_read_b128 v[132:135], v5 offset:880
	ds_read_b128 v[136:139], v5 offset:896
	ds_read_b128 v[140:143], v5 offset:912
	ds_read_b128 v[144:147], v5 offset:1008
	ds_read_b128 v[148:151], v5 offset:1024
	ds_read_b128 v[152:155], v5 offset:1040
	ds_read_b128 v[156:159], v5 offset:1056
	s_add_u32 s26, s26, 0x2000
	s_addc_u32 s27, s27, 0
	s_addk_i32 s22, 0x480
	s_cmp_eq_u32 s26, 0x40000
	s_waitcnt lgkmcnt(14)
; #define LAS __attribute__((address_space(3)))
; __device__ __forceinline__ void phase_convert(PP p, int l, LAS unsigned char* lds, int tid, int lane, int wave) {
;     ...
; #pragma unroll 8
;             for (int c = 0; c < 256; ++c) { const float bw = pw[c * 256];
; #pragma unroll
;                 for (int q = 0; q < 4; ++q) { const f32x4 a4 = *(const LAS f32x4*)(AtT + c * 36 + kh + 4 * q);
;                     acc[4 * q] += a4.x * bw; acc[4 * q + 1] += a4.y * bw; acc[4 * q + 2] += a4.z * bw; acc[4 * q + 3] += a4.w * bw; } }
;             u32x4 o0, o1;
;             o0.x = cvtpk(acc[0], acc[1]); o0.y = cvtpk(acc[2], acc[3]); o0.z = cvtpk(acc[4], acc[5]); o0.w = cvtpk(acc[6], acc[7]);
;             o1.x = cvtpk(acc[8], acc[9]); o1.y = cvtpk(acc[10], acc[11]); o1.z = cvtpk(acc[12], acc[13]); o1.w = cvtpk(acc[14], acc[15]);
;             bf16_t* wo = WMAIN + (size_t)(g * 256 + d) * DM + k0 + kh;
;             *(u32x4*)wo = o0; *(u32x4*)(wo + 8) = o1;
;             __syncthreads();
	v_pk_fma_f32 v[16:17], v[160:161], v[32:33], v[16:17] op_sel_hi:[0,1,1]
	v_pk_fma_f32 v[20:21], v[160:161], v[34:35], v[20:21] op_sel_hi:[0,1,1]
	v_pk_fma_f32 v[24:25], v[160:161], v[36:37], v[24:25] op_sel_hi:[0,1,1]
	v_pk_fma_f32 v[26:27], v[160:161], v[38:39], v[26:27] op_sel_hi:[0,1,1]
	v_pk_fma_f32 v[14:15], v[160:161], v[40:41], v[14:15] op_sel_hi:[0,1,1]
	v_pk_fma_f32 v[18:19], v[160:161], v[42:43], v[18:19] op_sel_hi:[0,1,1]
	v_pk_fma_f32 v[22:23], v[160:161], v[44:45], v[22:23] op_sel_hi:[0,1,1]
	v_pk_fma_f32 v[12:13], v[160:161], v[46:47], v[12:13] op_sel_hi:[0,1,1]
	v_pk_fma_f32 v[16:17], v[162:163], v[48:49], v[16:17] op_sel_hi:[0,1,1]
	v_pk_fma_f32 v[20:21], v[162:163], v[50:51], v[20:21] op_sel_hi:[0,1,1]
	v_pk_fma_f32 v[24:25], v[162:163], v[52:53], v[24:25] op_sel_hi:[0,1,1]
	v_pk_fma_f32 v[26:27], v[162:163], v[54:55], v[26:27] op_sel_hi:[0,1,1]
	v_pk_fma_f32 v[14:15], v[162:163], v[56:57], v[14:15] op_sel_hi:[0,1,1]
	v_pk_fma_f32 v[18:19], v[162:163], v[58:59], v[18:19] op_sel_hi:[0,1,1]
	v_pk_fma_f32 v[22:23], v[162:163], v[60:61], v[22:23] op_sel_hi:[0,1,1]
	v_pk_fma_f32 v[12:13], v[162:163], v[62:63], v[12:13] op_sel_hi:[0,1,1]
	v_pk_fma_f32 v[16:17], v[164:165], v[64:65], v[16:17] op_sel_hi:[0,1,1]
	v_pk_fma_f32 v[20:21], v[164:165], v[66:67], v[20:21] op_sel_hi:[0,1,1]
	v_pk_fma_f32 v[24:25], v[164:165], v[68:69], v[24:25] op_sel_hi:[0,1,1]
	v_pk_fma_f32 v[26:27], v[164:165], v[70:71], v[26:27] op_sel_hi:[0,1,1]
	v_pk_fma_f32 v[14:15], v[164:165], v[72:73], v[14:15] op_sel_hi:[0,1,1]
	v_pk_fma_f32 v[18:19], v[164:165], v[74:75], v[18:19] op_sel_hi:[0,1,1]
	v_pk_fma_f32 v[22:23], v[164:165], v[76:77], v[22:23] op_sel_hi:[0,1,1]
	v_pk_fma_f32 v[12:13], v[164:165], v[78:79], v[12:13] op_sel_hi:[0,1,1]
	v_pk_fma_f32 v[16:17], v[166:167], v[80:81], v[16:17] op_sel_hi:[0,1,1]
	v_pk_fma_f32 v[20:21], v[166:167], v[82:83], v[20:21] op_sel_hi:[0,1,1]
	v_pk_fma_f32 v[24:25], v[166:167], v[84:85], v[24:25] op_sel_hi:[0,1,1]
	v_pk_fma_f32 v[26:27], v[166:167], v[86:87], v[26:27] op_sel_hi:[0,1,1]
	v_pk_fma_f32 v[14:15], v[166:167], v[88:89], v[14:15] op_sel_hi:[0,1,1]
	v_pk_fma_f32 v[18:19], v[166:167], v[90:91], v[18:19] op_sel_hi:[0,1,1]
	v_pk_fma_f32 v[22:23], v[166:167], v[92:93], v[22:23] op_sel_hi:[0,1,1]
	v_pk_fma_f32 v[12:13], v[166:167], v[94:95], v[12:13] op_sel_hi:[0,1,1]
	v_pk_fma_f32 v[16:17], v[168:169], v[96:97], v[16:17] op_sel_hi:[0,1,1]
	v_pk_fma_f32 v[20:21], v[168:169], v[98:99], v[20:21] op_sel_hi:[0,1,1]
	v_pk_fma_f32 v[24:25], v[168:169], v[100:101], v[24:25] op_sel_hi:[0,1,1]
	v_pk_fma_f32 v[26:27], v[168:169], v[102:103], v[26:27] op_sel_hi:[0,1,1]
	s_waitcnt lgkmcnt(13)
	v_pk_fma_f32 v[14:15], v[168:169], v[104:105], v[14:15] op_sel_hi:[0,1,1]
	v_pk_fma_f32 v[18:19], v[168:169], v[106:107], v[18:19] op_sel_hi:[0,1,1]
	s_waitcnt lgkmcnt(12)
	v_pk_fma_f32 v[22:23], v[168:169], v[108:109], v[22:23] op_sel_hi:[0,1,1]
	v_pk_fma_f32 v[12:13], v[168:169], v[110:111], v[12:13] op_sel_hi:[0,1,1]
	s_waitcnt lgkmcnt(11)
	v_pk_fma_f32 v[16:17], v[170:171], v[112:113], v[16:17] op_sel_hi:[0,1,1]
	v_pk_fma_f32 v[20:21], v[170:171], v[114:115], v[20:21] op_sel_hi:[0,1,1]
	s_waitcnt lgkmcnt(10)
	v_pk_fma_f32 v[24:25], v[170:171], v[116:117], v[24:25] op_sel_hi:[0,1,1]
	v_pk_fma_f32 v[26:27], v[170:171], v[118:119], v[26:27] op_sel_hi:[0,1,1]
	s_waitcnt lgkmcnt(9)
	v_pk_fma_f32 v[14:15], v[170:171], v[120:121], v[14:15] op_sel_hi:[0,1,1]
	v_pk_fma_f32 v[18:19], v[170:171], v[122:123], v[18:19] op_sel_hi:[0,1,1]
	s_waitcnt lgkmcnt(8)
	v_pk_fma_f32 v[22:23], v[170:171], v[124:125], v[22:23] op_sel_hi:[0,1,1]
	v_pk_fma_f32 v[12:13], v[170:171], v[126:127], v[12:13] op_sel_hi:[0,1,1]
	s_waitcnt lgkmcnt(7)
	v_pk_fma_f32 v[16:17], v[172:173], v[128:129], v[16:17] op_sel_hi:[0,1,1]
	v_pk_fma_f32 v[20:21], v[172:173], v[130:131], v[20:21] op_sel_hi:[0,1,1]
	s_waitcnt lgkmcnt(6)
	v_pk_fma_f32 v[24:25], v[172:173], v[132:133], v[24:25] op_sel_hi:[0,1,1]
	v_pk_fma_f32 v[26:27], v[172:173], v[134:135], v[26:27] op_sel_hi:[0,1,1]
	s_waitcnt lgkmcnt(5)
	v_pk_fma_f32 v[14:15], v[172:173], v[136:137], v[14:15] op_sel_hi:[0,1,1]
	v_pk_fma_f32 v[18:19], v[172:173], v[138:139], v[18:19] op_sel_hi:[0,1,1]
	s_waitcnt lgkmcnt(4)
	v_pk_fma_f32 v[22:23], v[172:173], v[140:141], v[22:23] op_sel_hi:[0,1,1]
	v_pk_fma_f32 v[12:13], v[172:173], v[142:143], v[12:13] op_sel_hi:[0,1,1]
	s_waitcnt lgkmcnt(3)
	v_pk_fma_f32 v[16:17], v[174:175], v[144:145], v[16:17] op_sel_hi:[0,1,1]
	v_pk_fma_f32 v[20:21], v[174:175], v[146:147], v[20:21] op_sel_hi:[0,1,1]
	s_waitcnt lgkmcnt(2)
	v_pk_fma_f32 v[24:25], v[174:175], v[148:149], v[24:25] op_sel_hi:[0,1,1]
	v_pk_fma_f32 v[26:27], v[174:175], v[150:151], v[26:27] op_sel_hi:[0,1,1]
	s_waitcnt lgkmcnt(1)
	v_pk_fma_f32 v[14:15], v[174:175], v[152:153], v[14:15] op_sel_hi:[0,1,1]
	v_pk_fma_f32 v[18:19], v[174:175], v[154:155], v[18:19] op_sel_hi:[0,1,1]
	s_waitcnt lgkmcnt(0)
	v_pk_fma_f32 v[22:23], v[174:175], v[156:157], v[22:23] op_sel_hi:[0,1,1]
	v_pk_fma_f32 v[12:13], v[174:175], v[158:159], v[12:13] op_sel_hi:[0,1,1]
	s_cbranch_scc0 .LBB0_40
	s_waitcnt vmcnt(0)
	v_lshl_add_u32 v10, s25, 8, v4
	v_ashrrev_i32_e32 v11, 31, v10
	v_lshlrev_b64 v[10:11], 12, v[10:11]
	v_lshl_add_u64 v[10:11], s[18:19], 0, v[10:11]
	s_ashr_i32 s25, s24, 31
	v_lshl_add_u64 v[10:11], s[24:25], 1, v[10:11]
	s_add_i32 s39, s39, s70
	s_add_i32 s38, s38, s70
	v_cvt_pk_bf16_f32 v32, v16, v17
	v_cvt_pk_bf16_f32 v33, v20, v21
	v_cvt_pk_bf16_f32 v34, v24, v25
	v_cvt_pk_bf16_f32 v35, v26, v27
	v_lshl_add_u64 v[10:11], s[20:21], 1, v[10:11]
	s_cmpk_gt_i32 s39, 0xff
	v_cvt_pk_bf16_f32 v14, v14, v15
	v_cvt_pk_bf16_f32 v15, v18, v19
	v_cvt_pk_bf16_f32 v16, v22, v23
	v_cvt_pk_bf16_f32 v17, v12, v13
	global_store_dwordx4 v[10:11], v[32:35], off
	global_store_dwordx4 v[10:11], v[14:17], off offset:16
	s_barrier
	s_cbranch_scc0 .LBB0_27

; #define LAS __attribute__((address_space(3)))
; __device__ __forceinline__ void phase_convert(PP p, int l, LAS unsigned char* lds, int tid, int lane, int wave) {
;     ...
;         for (int item = blockIdx.x; item < 256; item += gridDim.x) {
;             const int kb = item >> 2, g = item & 3, k0 = kb * 32;
;             for (int i = tid; i < 32 * 256; i += 512) { const int r = i >> 8, cc = i & 255; AtT[cc * 36 + r] = w_in[(size_t)(k0 + r) * INP + g * 256 + cc]; }
;             __syncthreads();
;             const int d = (wave & 3) * 64 + lane, kh = (wave >> 2) * 16;
;             float acc[16];
; #pragma unroll
;             for (int e = 0; e < 16; ++e) acc[e] = 0.f;
;             const float* pw = pool_w + (size_t)g * 65536 + d;
; #pragma unroll 8
;             for (int c = 0; c < 256; ++c) { const float bw = pw[c * 256];
; #pragma unroll
;                 for (int q = 0; q < 4; ++q) { const f32x4 a4 = *(const LAS f32x4*)(AtT + c * 36 + kh + 4 * q);
;                     acc[4 * q] += a4.x * bw; acc[4 * q + 1] += a4.y * bw; acc[4 * q + 2] += a4.z * bw; acc[4 * q + 3] += a4.w * bw; } }
.LBB0_101:
	s_or_b64 exec, exec, s[22:23]
	s_and_b32 s6, s30, 3
	s_lshl_b32 s76, s6, 18
	v_mov_b32_e32 v14, 0
	v_lshl_add_u64 v[8:9], v[6:7], 0, s[76:77]
	s_mov_b64 s[22:23], 0
	s_mov_b32 s24, s29
	v_mov_b32_e32 v15, v14
	v_mov_b32_e32 v28, v14
	v_mov_b32_e32 v29, v14
	v_mov_b32_e32 v30, v14
	v_mov_b32_e32 v31, v14
	v_mov_b32_e32 v24, v14
	v_mov_b32_e32 v25, v14
	v_mov_b32_e32 v26, v14
	v_mov_b32_e32 v27, v14
	v_mov_b32_e32 v20, v14
	v_mov_b32_e32 v21, v14
	v_mov_b32_e32 v22, v14
	v_mov_b32_e32 v23, v14
	v_mov_b32_e32 v18, v14
	v_mov_b32_e32 v19, v14
	s_waitcnt lgkmcnt(0)
	s_barrier
	s_mov_b32 s100, 0x101000
	s_mov_b32 s101, 0
	v_lshl_add_u64 v[188:189], v[8:9], 0, s[22:23]
	v_lshl_add_u64 v[188:189], v[188:189], 0, s[100:101]
	global_load_dword v180, v[188:189], off offset:-4096
	global_load_dword v181, v[188:189], off offset:-3072
	global_load_dword v182, v[188:189], off offset:-2048
	global_load_dword v183, v[188:189], off offset:-1024
	global_load_dword v184, v[188:189], off offset:0
	global_load_dword v185, v[188:189], off offset:1024
	global_load_dword v186, v[188:189], off offset:2048
	global_load_dword v187, v[188:189], off offset:3072
.LBB0_102:
	s_waitcnt vmcnt(0)
	v_mov_b32_e32 v80, v180
	v_mov_b32_e32 v84, v181
	v_mov_b32_e32 v86, v182
	v_mov_b32_e32 v78, v183
	v_mov_b32_e32 v82, v184
	v_mov_b32_e32 v16, v185
	v_mov_b32_e32 v12, v186
	v_mov_b32_e32 v10, v187
	s_add_u32 s98, s22, 0x2000
	s_cmp_eq_u32 s98, 0x40000
	s_cselect_b32 s98, s22, s98
	s_mov_b32 s99, 0
	v_lshl_add_u64 v[188:189], v[8:9], 0, s[98:99]
	v_lshl_add_u64 v[188:189], v[188:189], 0, s[100:101]
	global_load_dword v180, v[188:189], off offset:-4096
	global_load_dword v181, v[188:189], off offset:-3072
	global_load_dword v182, v[188:189], off offset:-2048
	global_load_dword v183, v[188:189], off offset:-1024
	global_load_dword v184, v[188:189], off offset:0
	global_load_dword v185, v[188:189], off offset:1024
	global_load_dword v186, v[188:189], off offset:2048
	global_load_dword v187, v[188:189], off offset:3072
	v_mov_b32_e32 v3, s24
	s_nop 0
	s_nop 0
	ds_read_b128 v[34:37], v3
	ds_read_b128 v[38:41], v3 offset:16
	ds_read_b128 v[42:45], v3 offset:32
	ds_read_b128 v[46:49], v3 offset:48
	ds_read_b128 v[50:53], v3 offset:144
	ds_read_b128 v[54:57], v3 offset:160
	ds_read_b128 v[58:61], v3 offset:176
	ds_read_b128 v[62:65], v3 offset:192
	ds_read_b128 v[66:69], v3 offset:288
	ds_read_b128 v[70:73], v3 offset:304
	ds_read_b128 v[74:77], v3 offset:320
	s_nop 0
	s_nop 0
	s_nop 0
	s_add_u32 s22, s22, 0x2000
	s_addc_u32 s23, s23, 0
	s_addk_i32 s24, 0x480
	s_cmp_eq_u32 s22, 0x40000
	s_waitcnt lgkmcnt(10)
	v_pk_fma_f32 v[34:35], v[80:81], v[34:35], v[28:29] op_sel_hi:[0,1,1]
	v_pk_fma_f32 v[36:37], v[80:81], v[36:37], v[30:31] op_sel_hi:[0,1,1]
	s_waitcnt lgkmcnt(9)
	v_pk_fma_f32 v[38:39], v[80:81], v[38:39], v[24:25] op_sel_hi:[0,1,1]
	v_pk_fma_f32 v[40:41], v[80:81], v[40:41], v[26:27] op_sel_hi:[0,1,1]
	ds_read_b128 v[24:27], v3 offset:336
	s_waitcnt lgkmcnt(9)
	v_pk_fma_f32 v[42:43], v[80:81], v[42:43], v[20:21] op_sel_hi:[0,1,1]
	v_pk_fma_f32 v[44:45], v[80:81], v[44:45], v[22:23] op_sel_hi:[0,1,1]
	ds_read_b128 v[20:23], v3 offset:432
	s_waitcnt lgkmcnt(9)
	v_pk_fma_f32 v[18:19], v[80:81], v[46:47], v[18:19] op_sel_hi:[0,1,1]
	v_pk_fma_f32 v[14:15], v[80:81], v[48:49], v[14:15] op_sel_hi:[0,1,1]
	ds_read_b128 v[28:31], v3 offset:448
	s_waitcnt lgkmcnt(9)
	v_pk_fma_f32 v[80:81], v[84:85], v[50:51], v[34:35] op_sel_hi:[0,1,1]
	v_pk_fma_f32 v[88:89], v[84:85], v[52:53], v[36:37] op_sel_hi:[0,1,1]
	ds_read_b128 v[34:37], v3 offset:464
	s_waitcnt lgkmcnt(9)
	v_pk_fma_f32 v[90:91], v[84:85], v[54:55], v[38:39] op_sel_hi:[0,1,1]
	v_pk_fma_f32 v[92:93], v[84:85], v[56:57], v[40:41] op_sel_hi:[0,1,1]
	ds_read_b128 v[38:41], v3 offset:480
	s_waitcnt lgkmcnt(9)
	v_pk_fma_f32 v[94:95], v[84:85], v[58:59], v[42:43] op_sel_hi:[0,1,1]
	v_pk_fma_f32 v[96:97], v[84:85], v[60:61], v[44:45] op_sel_hi:[0,1,1]
	ds_read_b128 v[42:45], v3 offset:576
	ds_read_b128 v[46:49], v3 offset:592
	ds_read_b128 v[50:53], v3 offset:608
	ds_read_b128 v[54:57], v3 offset:624
	ds_read_b128 v[58:61], v3 offset:720
	s_waitcnt lgkmcnt(13)
	v_pk_fma_f32 v[18:19], v[84:85], v[62:63], v[18:19] op_sel_hi:[0,1,1]
	v_pk_fma_f32 v[14:15], v[84:85], v[64:65], v[14:15] op_sel_hi:[0,1,1]
	s_waitcnt lgkmcnt(12)
	v_pk_fma_f32 v[66:67], v[86:87], v[66:67], v[80:81] op_sel_hi:[0,1,1]
	v_pk_fma_f32 v[68:69], v[86:87], v[68:69], v[88:89] op_sel_hi:[0,1,1]
	s_waitcnt lgkmcnt(11)
	v_pk_fma_f32 v[70:71], v[86:87], v[70:71], v[90:91] op_sel_hi:[0,1,1]
	v_pk_fma_f32 v[72:73], v[86:87], v[72:73], v[92:93] op_sel_hi:[0,1,1]
	s_waitcnt lgkmcnt(10)
; #define LAS __attribute__((address_space(3)))
; __device__ __forceinline__ void phase_convert(PP p, int l, LAS unsigned char* lds, int tid, int lane, int wave) {
;     ...
; #pragma unroll 8
;             for (int c = 0; c < 256; ++c) { const float bw = pw[c * 256];
; #pragma unroll
;                 for (int q = 0; q < 4; ++q) { const f32x4 a4 = *(const LAS f32x4*)(AtT + c * 36 + kh + 4 * q);
;                     acc[4 * q] += a4.x * bw; acc[4 * q + 1] += a4.y * bw; acc[4 * q + 2] += a4.z * bw; acc[4 * q + 3] += a4.w * bw; } }
;             u32x4 o0, o1;
;             o0.x = cvtpk(acc[0], acc[1]); o0.y = cvtpk(acc[2], acc[3]); o0.z = cvtpk(acc[4], acc[5]); o0.w = cvtpk(acc[6], acc[7]);
;             o1.x = cvtpk(acc[8], acc[9]); o1.y = cvtpk(acc[10], acc[11]); o1.z = cvtpk(acc[12], acc[13]); o1.w = cvtpk(acc[14], acc[15]);
;             bf16_t* wo = WMAIN + (size_t)(g * 256 + d) * DM + k0 + kh;
;             *(u32x4*)wo = o0; *(u32x4*)(wo + 8) = o1;
;             __syncthreads();
	v_pk_fma_f32 v[74:75], v[86:87], v[74:75], v[94:95] op_sel_hi:[0,1,1]
	v_pk_fma_f32 v[76:77], v[86:87], v[76:77], v[96:97] op_sel_hi:[0,1,1]
	ds_read_b128 v[62:65], v3 offset:736
	s_waitcnt lgkmcnt(10)
	v_pk_fma_f32 v[80:81], v[86:87], v[24:25], v[18:19] op_sel_hi:[0,1,1]
	v_pk_fma_f32 v[14:15], v[86:87], v[26:27], v[14:15] op_sel_hi:[0,1,1]
	ds_read_b128 v[24:27], v3 offset:752
	s_waitcnt lgkmcnt(10)
	v_pk_fma_f32 v[84:85], v[78:79], v[20:21], v[66:67] op_sel_hi:[0,1,1]
	ds_read_b128 v[18:21], v3 offset:768
	v_pk_fma_f32 v[22:23], v[78:79], v[22:23], v[68:69] op_sel_hi:[0,1,1]
	s_waitcnt lgkmcnt(10)
	v_pk_fma_f32 v[70:71], v[78:79], v[28:29], v[70:71] op_sel_hi:[0,1,1]
	v_pk_fma_f32 v[72:73], v[78:79], v[30:31], v[72:73] op_sel_hi:[0,1,1]
	ds_read_b128 v[28:31], v3 offset:864
	s_waitcnt lgkmcnt(10)
	v_pk_fma_f32 v[74:75], v[78:79], v[34:35], v[74:75] op_sel_hi:[0,1,1]
	v_pk_fma_f32 v[76:77], v[78:79], v[36:37], v[76:77] op_sel_hi:[0,1,1]
	ds_read_b128 v[34:37], v3 offset:880
	s_waitcnt lgkmcnt(10)
	v_pk_fma_f32 v[80:81], v[78:79], v[38:39], v[80:81] op_sel_hi:[0,1,1]
	v_pk_fma_f32 v[14:15], v[78:79], v[40:41], v[14:15] op_sel_hi:[0,1,1]
	ds_read_b128 v[38:41], v3 offset:896
	ds_read_b128 v[66:69], v3 offset:912
	s_waitcnt lgkmcnt(11)
	v_pk_fma_f32 v[78:79], v[82:83], v[42:43], v[84:85] op_sel_hi:[0,1,1]
	v_pk_fma_f32 v[22:23], v[82:83], v[44:45], v[22:23] op_sel_hi:[0,1,1]
	ds_read_b128 v[42:45], v3 offset:1008
	s_waitcnt lgkmcnt(11)
	v_pk_fma_f32 v[70:71], v[82:83], v[46:47], v[70:71] op_sel_hi:[0,1,1]
	v_pk_fma_f32 v[72:73], v[82:83], v[48:49], v[72:73] op_sel_hi:[0,1,1]
	ds_read_b128 v[46:49], v3 offset:1024
	s_waitcnt lgkmcnt(11)
	v_pk_fma_f32 v[74:75], v[82:83], v[50:51], v[74:75] op_sel_hi:[0,1,1]
	v_pk_fma_f32 v[76:77], v[82:83], v[52:53], v[76:77] op_sel_hi:[0,1,1]
	ds_read_b128 v[50:53], v3 offset:1040
	s_waitcnt lgkmcnt(11)
	v_pk_fma_f32 v[80:81], v[82:83], v[54:55], v[80:81] op_sel_hi:[0,1,1]
	v_pk_fma_f32 v[14:15], v[82:83], v[56:57], v[14:15] op_sel_hi:[0,1,1]
	ds_read_b128 v[54:57], v3 offset:1056
	s_waitcnt lgkmcnt(11)
	v_pk_fma_f32 v[58:59], v[16:17], v[58:59], v[78:79] op_sel_hi:[0,1,1]
	v_pk_fma_f32 v[22:23], v[16:17], v[60:61], v[22:23] op_sel_hi:[0,1,1]
	s_waitcnt lgkmcnt(10)
	v_pk_fma_f32 v[60:61], v[16:17], v[62:63], v[70:71] op_sel_hi:[0,1,1]
	v_pk_fma_f32 v[62:63], v[16:17], v[64:65], v[72:73] op_sel_hi:[0,1,1]
	s_waitcnt lgkmcnt(9)
	v_pk_fma_f32 v[24:25], v[16:17], v[24:25], v[74:75] op_sel_hi:[0,1,1]
	v_pk_fma_f32 v[26:27], v[16:17], v[26:27], v[76:77] op_sel_hi:[0,1,1]
	s_waitcnt lgkmcnt(8)
	v_pk_fma_f32 v[18:19], v[16:17], v[18:19], v[80:81] op_sel_hi:[0,1,1]
	v_pk_fma_f32 v[14:15], v[16:17], v[20:21], v[14:15] op_sel_hi:[0,1,1]
	s_waitcnt lgkmcnt(7)
	v_pk_fma_f32 v[20:21], v[12:13], v[28:29], v[58:59] op_sel_hi:[0,1,1]
	v_pk_fma_f32 v[22:23], v[12:13], v[30:31], v[22:23] op_sel_hi:[0,1,1]
	s_waitcnt lgkmcnt(6)
	v_pk_fma_f32 v[34:35], v[12:13], v[34:35], v[60:61] op_sel_hi:[0,1,1]
	v_pk_fma_f32 v[36:37], v[12:13], v[36:37], v[62:63] op_sel_hi:[0,1,1]
	s_waitcnt lgkmcnt(5)
	v_pk_fma_f32 v[38:39], v[12:13], v[38:39], v[24:25] op_sel_hi:[0,1,1]
	v_pk_fma_f32 v[40:41], v[12:13], v[40:41], v[26:27] op_sel_hi:[0,1,1]
	s_waitcnt lgkmcnt(4)
	v_pk_fma_f32 v[18:19], v[12:13], v[66:67], v[18:19] op_sel_hi:[0,1,1]
	v_pk_fma_f32 v[14:15], v[12:13], v[68:69], v[14:15] op_sel_hi:[0,1,1]
	s_waitcnt lgkmcnt(3)
	v_pk_fma_f32 v[28:29], v[10:11], v[42:43], v[20:21] op_sel_hi:[0,1,1]
	v_pk_fma_f32 v[30:31], v[10:11], v[44:45], v[22:23] op_sel_hi:[0,1,1]
	s_waitcnt lgkmcnt(2)
	v_pk_fma_f32 v[24:25], v[10:11], v[46:47], v[34:35] op_sel_hi:[0,1,1]
	v_pk_fma_f32 v[26:27], v[10:11], v[48:49], v[36:37] op_sel_hi:[0,1,1]
	s_waitcnt lgkmcnt(1)
	v_pk_fma_f32 v[20:21], v[10:11], v[50:51], v[38:39] op_sel_hi:[0,1,1]
	v_pk_fma_f32 v[22:23], v[10:11], v[52:53], v[40:41] op_sel_hi:[0,1,1]
	s_waitcnt lgkmcnt(0)
	v_pk_fma_f32 v[18:19], v[10:11], v[54:55], v[18:19] op_sel_hi:[0,1,1]
	v_pk_fma_f32 v[14:15], v[10:11], v[56:57], v[14:15] op_sel_hi:[0,1,1]
	s_cbranch_scc0 .LBB0_102
	s_waitcnt vmcnt(0)
	v_cvt_pk_bf16_f32 v20, v20, v21
	v_cvt_pk_bf16_f32 v21, v22, v23
	v_cvt_pk_bf16_f32 v23, v14, v15
	v_lshl_add_u32 v14, s21, 8, v2
	v_ashrrev_i32_e32 v15, 31, v14
	v_lshlrev_b64 v[14:15], 12, v[14:15]
	v_lshl_add_u64 v[14:15], s[16:17], 0, v[14:15]
	s_ashr_i32 s21, s20, 31
	v_lshl_add_u64 v[14:15], s[20:21], 1, v[14:15]
	s_add_i32 s31, s31, s70
	s_add_i32 s30, s30, s70
	v_cvt_pk_bf16_f32 v8, v28, v29
	v_cvt_pk_bf16_f32 v9, v30, v31
	v_cvt_pk_bf16_f32 v10, v24, v25
	v_cvt_pk_bf16_f32 v11, v26, v27
	v_lshl_add_u64 v[14:15], s[18:19], 1, v[14:15]
	s_cmpk_gt_i32 s31, 0xff
	v_cvt_pk_bf16_f32 v22, v18, v19
	global_store_dwordx4 v[14:15], v[8:11], off
	global_store_dwordx4 v[14:15], v[20:23], off offset:16
	s_barrier
	s_cbranch_scc0 .LBB0_93
